# last phase epilogue: the sixteen residual-row loads of the eight row blocks issued together after the K loop (counted vmcnt waits per block)
# baseline (speedup 1.0000x reference)
; __device__ __forceinline__ float bf2f(unsigned b) { return __uint_as_float(b << 16); }
; #define PG8_WAIT_V(n) asm volatile("s_waitcnt vmcnt(" #n ")" ::: "memory")
; #define PG8_BAR __builtin_amdgcn_s_barrier()
;     ...
;     PG8_WAIT_V(0);
;     if constexpr (!ALIGN_EPI) { if (wr == 0) PG8_BAR; }
;     PG8_BAR;
;     __device__ __forceinline__ void fused(f32x4 (&acc)[2][2][4][2], const Unit& u, int wr, int wc, int fr, int fq, LAS unsigned char* lds, int wid, int lane) const {
;     ...
; #pragma unroll
;         for (int ai = 0; ai < 2; ++ai)
; #pragma unroll
;             for (int m = 0; m < 4; ++m) {
;                 const int r = ai * 128 + wr * 64 + m * 16 + fr; const size_t row = (size_t)u.pm * 256 + r;
;                 float ss = 0.f;
; #pragma unroll
;                 for (int bj = 0; bj < 2; ++bj) {
;                     const int col0 = u.pn * 256 + bj * 128 + wc * 32 + fq * 8;
;                     const v4u xb = __builtin_nontemporal_load((const v4u*)(XMIDB + row * D + col0));
;                     f32x4 v0 = acc[ai][bj][m][0], v1 = acc[ai][bj][m][1];
;                     v0[0] += bf2f(xb.x & 0xffffu); v0[1] += bf2f(xb.x >> 16); v0[2] += bf2f(xb.y & 0xffffu); v0[3] += bf2f(xb.y >> 16);
;                     v1[0] += bf2f(xb.z & 0xffffu); v1[1] += bf2f(xb.z >> 16); v1[2] += bf2f(xb.w & 0xffffu); v1[3] += bf2f(xb.w >> 16);
;                     acc[ai][bj][m][0] = v0; acc[ai][bj][m][1] = v1;
;                     ss += (v0[0] * v0[0] + v0[1] * v0[1]) + (v0[2] * v0[2] + v0[3] * v0[3]) + (v1[0] * v1[0] + v1[1] * v1[1]) + (v1[2] * v1[2] + v1[3] * v1[3]);
;                 }
;                 ss += __shfl_xor(ss, 16); ss += __shfl_xor(ss, 32);
;                 if (fq == 0) P[r * 4 + wc] = ss;
.LBB0_1209:
	s_lshl_b32 s0, s42, 5
	s_lshl_b32 s1, s12, 8
	v_lshrrev_b32_e32 v129, 1, v152
	s_ashr_i32 s9, s8, 31
	s_or_b32 s0, s1, s0
	s_lshl_b32 s2, s42, 2
	v_and_or_b32 v130, v129, 24, s0
	s_lshl_b64 s[0:1], s[8:9], 19
	s_add_i32 s14, s2, 0
	s_add_u32 s0, s10, s0
	s_addc_u32 s1, s11, s1
	v_ashrrev_i32_e32 v129, 31, v128
	s_add_u32 s0, s0, 0xb4c0000
	v_lshlrev_b64 v[132:133], 11, v[128:129]
	s_addc_u32 s1, s1, 0
	v_lshl_add_u64 v[132:133], s[0:1], 0, v[132:133]
	v_ashrrev_i32_e32 v131, 31, v130
	v_lshl_add_u64 v[136:137], v[130:131], 1, v[132:133]
	s_waitcnt vmcnt(0)
	s_barrier
	v_mov_b32_e32 v252, v128
	v_ashrrev_i32_e32 v253, 31, v252
	v_lshlrev_b64 v[252:253], 11, v[252:253]
	v_lshl_add_u64 v[252:253], s[0:1], 0, v[252:253]
	v_lshl_add_u64 v[252:253], v[130:131], 1, v[252:253]
	global_load_dwordx4 v[188:191], v[252:253], off nt
	global_load_dwordx4 v[192:195], v[252:253], off offset:256 nt
	v_or_b32_e32 v254, 16, v128
	v_ashrrev_i32_e32 v255, 31, v254
	v_lshlrev_b64 v[254:255], 11, v[254:255]
	v_lshl_add_u64 v[254:255], s[0:1], 0, v[254:255]
	v_lshl_add_u64 v[254:255], v[130:131], 1, v[254:255]
	global_load_dwordx4 v[196:199], v[254:255], off nt
	global_load_dwordx4 v[200:203], v[254:255], off offset:256 nt
	v_or_b32_e32 v252, 32, v128
	v_ashrrev_i32_e32 v253, 31, v252
	v_lshlrev_b64 v[252:253], 11, v[252:253]
	v_lshl_add_u64 v[252:253], s[0:1], 0, v[252:253]
	v_lshl_add_u64 v[252:253], v[130:131], 1, v[252:253]
	global_load_dwordx4 v[204:207], v[252:253], off nt
	global_load_dwordx4 v[208:211], v[252:253], off offset:256 nt
	v_or_b32_e32 v254, 48, v128
	v_ashrrev_i32_e32 v255, 31, v254
	v_lshlrev_b64 v[254:255], 11, v[254:255]
	v_lshl_add_u64 v[254:255], s[0:1], 0, v[254:255]
	v_lshl_add_u64 v[254:255], v[130:131], 1, v[254:255]
	global_load_dwordx4 v[212:215], v[254:255], off nt
	global_load_dwordx4 v[216:219], v[254:255], off offset:256 nt
	v_add_u32_e32 v252, 0x80, v128
	v_ashrrev_i32_e32 v253, 31, v252
	v_lshlrev_b64 v[252:253], 11, v[252:253]
	v_lshl_add_u64 v[252:253], s[0:1], 0, v[252:253]
	v_lshl_add_u64 v[252:253], v[130:131], 1, v[252:253]
	global_load_dwordx4 v[220:223], v[252:253], off nt
	global_load_dwordx4 v[224:227], v[252:253], off offset:256 nt
	v_add_u32_e32 v254, 0x90, v128
	v_ashrrev_i32_e32 v255, 31, v254
	v_lshlrev_b64 v[254:255], 11, v[254:255]
	v_lshl_add_u64 v[254:255], s[0:1], 0, v[254:255]
	v_lshl_add_u64 v[254:255], v[130:131], 1, v[254:255]
	global_load_dwordx4 v[228:231], v[254:255], off nt
	global_load_dwordx4 v[232:235], v[254:255], off offset:256 nt
	v_add_u32_e32 v252, 0xa0, v128
	v_ashrrev_i32_e32 v253, 31, v252
	v_lshlrev_b64 v[252:253], 11, v[252:253]
	v_lshl_add_u64 v[252:253], s[0:1], 0, v[252:253]
	v_lshl_add_u64 v[252:253], v[130:131], 1, v[252:253]
	global_load_dwordx4 v[236:239], v[252:253], off nt
	global_load_dwordx4 v[240:243], v[252:253], off offset:256 nt
	v_add_u32_e32 v254, 0xb0, v128
	v_ashrrev_i32_e32 v255, 31, v254
	v_lshlrev_b64 v[254:255], 11, v[254:255]
	v_lshl_add_u64 v[254:255], s[0:1], 0, v[254:255]
	v_lshl_add_u64 v[254:255], v[130:131], 1, v[254:255]
	global_load_dwordx4 v[244:247], v[254:255], off nt
	global_load_dwordx4 v[248:251], v[254:255], off offset:256 nt
	s_waitcnt vmcnt(14)
	v_mov_b32_e32 v132, v188
	v_mov_b32_e32 v133, v189
	v_mov_b32_e32 v134, v190
	v_mov_b32_e32 v135, v191
	v_mov_b32_e32 v136, v192
	v_mov_b32_e32 v137, v193
	v_mov_b32_e32 v138, v194
	v_mov_b32_e32 v139, v195
	v_mbcnt_hi_u32_b32 v148, -1, v155
	v_and_b32_e32 v141, 64, v148
	v_xor_b32_e32 v140, 16, v148
	v_add_u32_e32 v149, 64, v141
	v_cmp_lt_i32_e32 vcc, v140, v149
	v_and_b32_e32 v164, 63, v152
	v_and_b32_e32 v141, 0xffff0000, v132
	v_cndmask_b32_e32 v140, v148, v140, vcc
	v_lshlrev_b32_e32 v153, 2, v140
	v_lshlrev_b32_e32 v140, 16, v132
	v_lshlrev_b32_e32 v132, 16, v133
	v_and_b32_e32 v133, 0xffff0000, v133
	v_lshlrev_b32_e32 v144, 16, v136
	v_and_b32_e32 v145, 0xffff0000, v136
	v_lshlrev_b32_e32 v136, 16, v137
	v_and_b32_e32 v137, 0xffff0000, v137
	v_lshlrev_b32_e32 v142, 16, v134
	v_and_b32_e32 v143, 0xffff0000, v134
	v_lshlrev_b32_e32 v134, 16, v135
	v_and_b32_e32 v135, 0xffff0000, v135
	v_lshlrev_b32_e32 v146, 16, v138
	v_and_b32_e32 v147, 0xffff0000, v138
	v_pk_add_f32 v[124:125], v[124:125], v[140:141]
	v_pk_add_f32 v[126:127], v[126:127], v[132:133]
	v_pk_add_f32 v[116:117], v[116:117], v[144:145]
	v_pk_add_f32 v[118:119], v[118:119], v[136:137]
	v_lshlrev_b32_e32 v138, 16, v139
	v_and_b32_e32 v139, 0xffff0000, v139
	v_pk_add_f32 v[120:121], v[120:121], v[142:143]
	v_pk_add_f32 v[122:123], v[122:123], v[134:135]
	v_pk_add_f32 v[112:113], v[112:113], v[146:147]
	v_pk_mul_f32 v[132:133], v[124:125], v[124:125]
	v_pk_mul_f32 v[134:135], v[126:127], v[126:127]
	v_pk_mul_f32 v[140:141], v[116:117], v[116:117]
	v_pk_mul_f32 v[142:143], v[118:119], v[118:119]
	v_pk_add_f32 v[114:115], v[114:115], v[138:139]
	v_pk_mul_f32 v[136:137], v[120:121], v[120:121]
	v_pk_mul_f32 v[144:145], v[112:113], v[112:113]
	v_add_f32_e32 v142, v142, v143
	v_add_f32_e32 v140, v140, v141
	v_add_f32_e32 v134, v134, v135
	v_add_f32_e32 v132, v132, v133
	v_pk_mul_f32 v[138:139], v[122:123], v[122:123]
	v_pk_mul_f32 v[146:147], v[114:115], v[114:115]
	v_add_f32_e32 v141, v144, v145
	v_add_f32_e32 v133, v136, v137
	v_add_f32_e32 v135, v140, v142
	v_add_f32_e32 v132, v132, v134
	v_add_f32_e32 v146, v146, v147
	v_add_f32_e32 v138, v138, v139
	v_add_f32_e32 v134, v141, v135
	v_add_f32_e32 v132, v133, v132
	v_add_f32_e32 v133, v146, v134
	v_add_f32_e32 v132, v138, v132
	v_add_f32_e32 v132, v132, v133
	ds_bpermute_b32 v133, v153, v132
	v_xor_b32_e32 v134, 32, v148
	v_cmp_lt_i32_e32 vcc, v134, v149
	s_waitcnt lgkmcnt(0)
	v_add_f32_e32 v132, v132, v133
	v_cndmask_b32_e32 v134, v148, v134, vcc
	v_lshlrev_b32_e32 v165, 2, v134
	ds_bpermute_b32 v133, v165, v132
	v_cmp_gt_u32_e32 vcc, 16, v164
	s_and_saveexec_b64 s[2:3], vcc
	s_cbranch_execz .LBB0_1211
	v_lshl_add_u32 v134, v128, 4, s14
	s_waitcnt lgkmcnt(0)
	v_add_f32_e32 v132, v132, v133
	ds_write_b32 v134, v132
; __device__ __forceinline__ float bf2f(unsigned b) { return __uint_as_float(b << 16); }
;     __device__ __forceinline__ void fused(f32x4 (&acc)[2][2][4][2], const Unit& u, int wr, int wc, int fr, int fq, LAS unsigned char* lds, int wid, int lane) const {
;     ...
;             for (int m = 0; m < 4; ++m) {
;                 const int r = ai * 128 + wr * 64 + m * 16 + fr; const size_t row = (size_t)u.pm * 256 + r;
;                 float ss = 0.f;
; #pragma unroll
;                 for (int bj = 0; bj < 2; ++bj) {
;                     const int col0 = u.pn * 256 + bj * 128 + wc * 32 + fq * 8;
;                     const v4u xb = __builtin_nontemporal_load((const v4u*)(XMIDB + row * D + col0));
;                     f32x4 v0 = acc[ai][bj][m][0], v1 = acc[ai][bj][m][1];
;                     v0[0] += bf2f(xb.x & 0xffffu); v0[1] += bf2f(xb.x >> 16); v0[2] += bf2f(xb.y & 0xffffu); v0[3] += bf2f(xb.y >> 16);
;                     v1[0] += bf2f(xb.z & 0xffffu); v1[1] += bf2f(xb.z >> 16); v1[2] += bf2f(xb.w & 0xffffu); v1[3] += bf2f(xb.w >> 16);
;                     acc[ai][bj][m][0] = v0; acc[ai][bj][m][1] = v1;
;                     ss += (v0[0] * v0[0] + v0[1] * v0[1]) + (v0[2] * v0[2] + v0[3] * v0[3]) + (v1[0] * v1[0] + v1[1] * v1[1]) + (v1[2] * v1[2] + v1[3] * v1[3]);
;                 }
;                 ss += __shfl_xor(ss, 16); ss += __shfl_xor(ss, 32);
;                 if (fq == 0) P[r * 4 + wc] = ss;
;                 if (m == 3) asm volatile("" ::: "memory");
.LBB0_1211:
	s_or_b64 exec, exec, s[2:3]
	v_or_b32_e32 v132, 16, v128
	s_waitcnt lgkmcnt(0)
	v_ashrrev_i32_e32 v133, 31, v132
	v_lshlrev_b64 v[134:135], 11, v[132:133]
	v_lshl_add_u64 v[134:135], s[0:1], 0, v[134:135]
	v_lshl_add_u64 v[138:139], v[130:131], 1, v[134:135]
	s_waitcnt vmcnt(12)
	v_mov_b32_e32 v134, v196
	v_mov_b32_e32 v135, v197
	v_mov_b32_e32 v136, v198
	v_mov_b32_e32 v137, v199
	v_mov_b32_e32 v138, v200
	v_mov_b32_e32 v139, v201
	v_mov_b32_e32 v140, v202
	v_mov_b32_e32 v141, v203
	v_lshlrev_b32_e32 v142, 16, v134
	v_and_b32_e32 v143, 0xffff0000, v134
	v_lshlrev_b32_e32 v134, 16, v135
	v_and_b32_e32 v135, 0xffff0000, v135
	v_lshlrev_b32_e32 v146, 16, v138
	v_and_b32_e32 v147, 0xffff0000, v138
	v_lshlrev_b32_e32 v138, 16, v139
	v_and_b32_e32 v139, 0xffff0000, v139
	v_lshlrev_b32_e32 v144, 16, v136
	v_and_b32_e32 v145, 0xffff0000, v136
	v_lshlrev_b32_e32 v136, 16, v137
	v_and_b32_e32 v137, 0xffff0000, v137
	v_lshlrev_b32_e32 v148, 16, v140
	v_and_b32_e32 v149, 0xffff0000, v140
	v_pk_add_f32 v[108:109], v[108:109], v[142:143]
	v_pk_add_f32 v[110:111], v[110:111], v[134:135]
	v_pk_add_f32 v[100:101], v[100:101], v[146:147]
	v_pk_add_f32 v[102:103], v[102:103], v[138:139]
	v_lshlrev_b32_e32 v140, 16, v141
	v_and_b32_e32 v141, 0xffff0000, v141
	v_pk_add_f32 v[104:105], v[104:105], v[144:145]
	v_pk_add_f32 v[106:107], v[106:107], v[136:137]
	v_pk_add_f32 v[96:97], v[96:97], v[148:149]
	v_pk_mul_f32 v[134:135], v[108:109], v[108:109]
	v_pk_mul_f32 v[136:137], v[110:111], v[110:111]
	v_pk_mul_f32 v[142:143], v[100:101], v[100:101]
	v_pk_mul_f32 v[144:145], v[102:103], v[102:103]
	v_pk_add_f32 v[98:99], v[98:99], v[140:141]
	v_pk_mul_f32 v[138:139], v[104:105], v[104:105]
	v_pk_mul_f32 v[146:147], v[96:97], v[96:97]
	v_add_f32_e32 v144, v144, v145
	v_add_f32_e32 v142, v142, v143
	v_add_f32_e32 v136, v136, v137
	v_add_f32_e32 v134, v134, v135
	v_pk_mul_f32 v[140:141], v[106:107], v[106:107]
	v_pk_mul_f32 v[148:149], v[98:99], v[98:99]
	v_add_f32_e32 v143, v146, v147
	v_add_f32_e32 v135, v138, v139
	v_add_f32_e32 v137, v142, v144
	v_add_f32_e32 v134, v134, v136
	v_add_f32_e32 v148, v148, v149
	v_add_f32_e32 v140, v140, v141
	v_add_f32_e32 v136, v143, v137
	v_add_f32_e32 v134, v135, v134
	v_add_f32_e32 v135, v148, v136
	v_add_f32_e32 v134, v140, v134
	v_add_f32_e32 v134, v134, v135
	ds_bpermute_b32 v135, v153, v134
	s_waitcnt lgkmcnt(0)
	v_add_f32_e32 v134, v134, v135
	ds_bpermute_b32 v135, v165, v134
	s_and_saveexec_b64 s[2:3], vcc
	s_cbranch_execz .LBB0_1213
	v_lshl_add_u32 v136, v132, 4, s14
	s_waitcnt lgkmcnt(0)
	v_add_f32_e32 v134, v134, v135
	ds_write_b32 v136, v134
.LBB0_1213:
	s_or_b64 exec, exec, s[2:3]
	v_or_b32_e32 v134, 32, v128
	s_waitcnt lgkmcnt(0)
	v_ashrrev_i32_e32 v135, 31, v134
	v_lshlrev_b64 v[136:137], 11, v[134:135]
	v_lshl_add_u64 v[136:137], s[0:1], 0, v[136:137]
	v_lshl_add_u64 v[140:141], v[130:131], 1, v[136:137]
	s_waitcnt vmcnt(10)
	v_mov_b32_e32 v136, v204
	v_mov_b32_e32 v137, v205
	v_mov_b32_e32 v138, v206
	v_mov_b32_e32 v139, v207
	v_mov_b32_e32 v140, v208
	v_mov_b32_e32 v141, v209
	v_mov_b32_e32 v142, v210
	v_mov_b32_e32 v143, v211
	v_lshlrev_b32_e32 v144, 16, v136
	v_and_b32_e32 v145, 0xffff0000, v136
	v_lshlrev_b32_e32 v146, 16, v137
	v_and_b32_e32 v147, 0xffff0000, v137
	v_lshlrev_b32_e32 v148, 16, v138
	v_and_b32_e32 v149, 0xffff0000, v138
	v_lshlrev_b32_e32 v150, 16, v140
	v_and_b32_e32 v151, 0xffff0000, v140
	v_lshlrev_b32_e32 v140, 16, v141
	v_and_b32_e32 v141, 0xffff0000, v141
	v_lshlrev_b32_e32 v138, 16, v139
	v_and_b32_e32 v139, 0xffff0000, v139
	v_lshlrev_b32_e32 v154, 16, v142
	v_and_b32_e32 v155, 0xffff0000, v142
	v_pk_add_f32 v[136:137], v[92:93], v[144:145]
	v_pk_add_f32 v[94:95], v[94:95], v[146:147]
	v_pk_add_f32 v[92:93], v[88:89], v[148:149]
	v_pk_add_f32 v[88:89], v[84:85], v[150:151]
	v_pk_add_f32 v[86:87], v[86:87], v[140:141]
	v_lshlrev_b32_e32 v142, 16, v143
	v_and_b32_e32 v143, 0xffff0000, v143
	v_pk_add_f32 v[90:91], v[90:91], v[138:139]
	v_pk_add_f32 v[84:85], v[80:81], v[154:155]
	v_pk_mul_f32 v[80:81], v[136:137], v[136:137]
	v_pk_mul_f32 v[138:139], v[94:95], v[94:95]
	v_pk_mul_f32 v[144:145], v[88:89], v[88:89]
	v_pk_mul_f32 v[146:147], v[86:87], v[86:87]
	v_pk_add_f32 v[82:83], v[82:83], v[142:143]
	v_pk_mul_f32 v[140:141], v[92:93], v[92:93]
	v_pk_mul_f32 v[148:149], v[84:85], v[84:85]
	v_add_f32_e32 v146, v146, v147
	v_add_f32_e32 v144, v144, v145
	v_add_f32_e32 v138, v138, v139
	v_add_f32_e32 v80, v80, v81
	v_pk_mul_f32 v[142:143], v[90:91], v[90:91]
	v_pk_mul_f32 v[150:151], v[82:83], v[82:83]
	v_add_f32_e32 v145, v148, v149
	v_add_f32_e32 v81, v140, v141
	v_add_f32_e32 v139, v144, v146
	v_add_f32_e32 v80, v80, v138
	v_add_f32_e32 v150, v150, v151
	v_add_f32_e32 v142, v142, v143
	v_add_f32_e32 v138, v145, v139
	v_add_f32_e32 v80, v81, v80
	v_add_f32_e32 v81, v150, v138
	v_add_f32_e32 v80, v142, v80
	v_add_f32_e32 v80, v80, v81
	ds_bpermute_b32 v81, v153, v80
	s_waitcnt lgkmcnt(0)
	v_add_f32_e32 v80, v80, v81
	ds_bpermute_b32 v81, v165, v80
	s_and_saveexec_b64 s[2:3], vcc
	s_cbranch_execz .LBB0_1215
	v_lshl_add_u32 v138, v134, 4, s14
	s_waitcnt lgkmcnt(0)
	v_add_f32_e32 v80, v80, v81
	ds_write_b32 v138, v80
; __device__ __forceinline__ float bf2f(unsigned b) { return __uint_as_float(b << 16); }
;     __device__ __forceinline__ void fused(f32x4 (&acc)[2][2][4][2], const Unit& u, int wr, int wc, int fr, int fq, LAS unsigned char* lds, int wid, int lane) const {
;     ...
;             for (int m = 0; m < 4; ++m) {
;                 const int r = ai * 128 + wr * 64 + m * 16 + fr; const size_t row = (size_t)u.pm * 256 + r;
;                 float ss = 0.f;
; #pragma unroll
;                 for (int bj = 0; bj < 2; ++bj) {
;                     const int col0 = u.pn * 256 + bj * 128 + wc * 32 + fq * 8;
;                     const v4u xb = __builtin_nontemporal_load((const v4u*)(XMIDB + row * D + col0));
;                     f32x4 v0 = acc[ai][bj][m][0], v1 = acc[ai][bj][m][1];
;                     v0[0] += bf2f(xb.x & 0xffffu); v0[1] += bf2f(xb.x >> 16); v0[2] += bf2f(xb.y & 0xffffu); v0[3] += bf2f(xb.y >> 16);
;                     v1[0] += bf2f(xb.z & 0xffffu); v1[1] += bf2f(xb.z >> 16); v1[2] += bf2f(xb.w & 0xffffu); v1[3] += bf2f(xb.w >> 16);
;                     acc[ai][bj][m][0] = v0; acc[ai][bj][m][1] = v1;
;                     ss += (v0[0] * v0[0] + v0[1] * v0[1]) + (v0[2] * v0[2] + v0[3] * v0[3]) + (v1[0] * v1[0] + v1[1] * v1[1]) + (v1[2] * v1[2] + v1[3] * v1[3]);
;                 }
;                 ss += __shfl_xor(ss, 16); ss += __shfl_xor(ss, 32);
;                 if (fq == 0) P[r * 4 + wc] = ss;
;                 if (m == 3) asm volatile("" ::: "memory");
.LBB0_1215:
	s_or_b64 exec, exec, s[2:3]
	v_or_b32_e32 v80, 48, v128
	s_waitcnt lgkmcnt(0)
	v_ashrrev_i32_e32 v81, 31, v80
	v_lshlrev_b64 v[138:139], 11, v[80:81]
	v_lshl_add_u64 v[138:139], s[0:1], 0, v[138:139]
	v_lshl_add_u64 v[142:143], v[130:131], 1, v[138:139]
	s_waitcnt vmcnt(8)
	v_mov_b32_e32 v138, v212
	v_mov_b32_e32 v139, v213
	v_mov_b32_e32 v140, v214
	v_mov_b32_e32 v141, v215
	v_mov_b32_e32 v142, v216
	v_mov_b32_e32 v143, v217
	v_mov_b32_e32 v144, v218
	v_mov_b32_e32 v145, v219
	v_lshlrev_b32_e32 v146, 16, v138
	v_and_b32_e32 v147, 0xffff0000, v138
	v_lshlrev_b32_e32 v148, 16, v139
	v_and_b32_e32 v149, 0xffff0000, v139
	v_lshlrev_b32_e32 v150, 16, v140
	v_and_b32_e32 v151, 0xffff0000, v140
	v_lshlrev_b32_e32 v154, 16, v142
	v_and_b32_e32 v155, 0xffff0000, v142
	v_lshlrev_b32_e32 v142, 16, v143
	v_and_b32_e32 v143, 0xffff0000, v143
	v_lshlrev_b32_e32 v140, 16, v141
	v_and_b32_e32 v141, 0xffff0000, v141
	v_lshlrev_b32_e32 v156, 16, v144
	v_and_b32_e32 v157, 0xffff0000, v144
	v_lshlrev_b32_e32 v144, 16, v145
	v_and_b32_e32 v145, 0xffff0000, v145
	v_pk_add_f32 v[138:139], v[76:77], v[146:147]
	v_pk_add_f32 v[78:79], v[78:79], v[148:149]
	v_pk_add_f32 v[76:77], v[72:73], v[150:151]
	v_pk_add_f32 v[72:73], v[68:69], v[154:155]
	v_pk_add_f32 v[70:71], v[70:71], v[142:143]
	v_pk_add_f32 v[74:75], v[74:75], v[140:141]
	v_pk_add_f32 v[68:69], v[64:65], v[156:157]
	v_pk_add_f32 v[64:65], v[66:67], v[144:145]
	v_pk_mul_f32 v[66:67], v[138:139], v[138:139]
	v_pk_mul_f32 v[140:141], v[78:79], v[78:79]
	v_pk_mul_f32 v[146:147], v[72:73], v[72:73]
	v_pk_mul_f32 v[148:149], v[70:71], v[70:71]
	v_pk_mul_f32 v[142:143], v[76:77], v[76:77]
	v_pk_mul_f32 v[150:151], v[68:69], v[68:69]
	v_add_f32_e32 v148, v148, v149
	v_add_f32_e32 v146, v146, v147
	v_add_f32_e32 v140, v140, v141
	v_add_f32_e32 v66, v66, v67
	v_pk_mul_f32 v[144:145], v[74:75], v[74:75]
	v_pk_mul_f32 v[154:155], v[64:65], v[64:65]
	v_add_f32_e32 v147, v150, v151
	v_add_f32_e32 v67, v142, v143
	v_add_f32_e32 v141, v146, v148
	v_add_f32_e32 v66, v66, v140
	v_add_f32_e32 v154, v154, v155
	v_add_f32_e32 v144, v144, v145
	v_add_f32_e32 v140, v147, v141
	v_add_f32_e32 v66, v67, v66
	v_add_f32_e32 v67, v154, v140
	v_add_f32_e32 v66, v144, v66
	v_add_f32_e32 v66, v66, v67
	ds_bpermute_b32 v67, v153, v66
	s_waitcnt lgkmcnt(0)
	v_add_f32_e32 v66, v66, v67
	ds_bpermute_b32 v67, v165, v66
	s_and_saveexec_b64 s[2:3], vcc
	s_cbranch_execz .LBB0_1217
	v_lshl_add_u32 v140, v80, 4, s14
	s_waitcnt lgkmcnt(0)
	v_add_f32_e32 v66, v66, v67
	ds_write_b32 v140, v66
.LBB0_1217:
	s_or_b64 exec, exec, s[2:3]
	v_add_u32_e32 v66, 0x80, v128
	s_waitcnt lgkmcnt(0)
	v_ashrrev_i32_e32 v67, 31, v66
	v_lshlrev_b64 v[140:141], 11, v[66:67]
	v_lshl_add_u64 v[140:141], s[0:1], 0, v[140:141]
	v_lshl_add_u64 v[144:145], v[130:131], 1, v[140:141]
	s_waitcnt vmcnt(6)
	v_mov_b32_e32 v140, v220
	v_mov_b32_e32 v141, v221
	v_mov_b32_e32 v142, v222
	v_mov_b32_e32 v143, v223
	v_mov_b32_e32 v144, v224
	v_mov_b32_e32 v145, v225
	v_mov_b32_e32 v146, v226
	v_mov_b32_e32 v147, v227
	v_lshlrev_b32_e32 v148, 16, v140
	v_and_b32_e32 v149, 0xffff0000, v140
	v_lshlrev_b32_e32 v140, 16, v141
	v_and_b32_e32 v141, 0xffff0000, v141
	v_lshlrev_b32_e32 v154, 16, v144
	v_and_b32_e32 v155, 0xffff0000, v144
	v_lshlrev_b32_e32 v144, 16, v145
	v_and_b32_e32 v145, 0xffff0000, v145
	v_lshlrev_b32_e32 v150, 16, v142
	v_and_b32_e32 v151, 0xffff0000, v142
	v_lshlrev_b32_e32 v142, 16, v143
	v_and_b32_e32 v143, 0xffff0000, v143
	v_lshlrev_b32_e32 v156, 16, v146
	v_and_b32_e32 v157, 0xffff0000, v146
	v_pk_add_f32 v[60:61], v[60:61], v[148:149]
	v_pk_add_f32 v[62:63], v[62:63], v[140:141]
	v_pk_add_f32 v[52:53], v[52:53], v[154:155]
	v_pk_add_f32 v[54:55], v[54:55], v[144:145]
	v_lshlrev_b32_e32 v146, 16, v147
	v_and_b32_e32 v147, 0xffff0000, v147
	v_pk_add_f32 v[56:57], v[56:57], v[150:151]
	v_pk_add_f32 v[58:59], v[58:59], v[142:143]
	v_pk_add_f32 v[48:49], v[48:49], v[156:157]
	v_pk_mul_f32 v[140:141], v[60:61], v[60:61]
	v_pk_mul_f32 v[142:143], v[62:63], v[62:63]
	v_pk_mul_f32 v[148:149], v[52:53], v[52:53]
	v_pk_mul_f32 v[150:151], v[54:55], v[54:55]
	v_pk_add_f32 v[50:51], v[50:51], v[146:147]
	v_pk_mul_f32 v[144:145], v[56:57], v[56:57]
	v_pk_mul_f32 v[154:155], v[48:49], v[48:49]
	v_add_f32_e32 v150, v150, v151
	v_add_f32_e32 v148, v148, v149
	v_add_f32_e32 v142, v142, v143
	v_add_f32_e32 v140, v140, v141
	v_pk_mul_f32 v[146:147], v[58:59], v[58:59]
	v_pk_mul_f32 v[156:157], v[50:51], v[50:51]
	v_add_f32_e32 v149, v154, v155
	v_add_f32_e32 v141, v144, v145
	v_add_f32_e32 v143, v148, v150
	v_add_f32_e32 v140, v140, v142
	v_add_f32_e32 v156, v156, v157
	v_add_f32_e32 v146, v146, v147
	v_add_f32_e32 v142, v149, v143
	v_add_f32_e32 v140, v141, v140
	v_add_f32_e32 v141, v156, v142
	v_add_f32_e32 v140, v146, v140
	v_add_f32_e32 v140, v140, v141
	ds_bpermute_b32 v141, v153, v140
	s_waitcnt lgkmcnt(0)
	v_add_f32_e32 v140, v140, v141
	ds_bpermute_b32 v141, v165, v140
	s_and_saveexec_b64 s[2:3], vcc
	s_cbranch_execz .LBB0_1219
	v_lshl_add_u32 v142, v66, 4, s14
	s_waitcnt lgkmcnt(0)
	v_add_f32_e32 v140, v140, v141
	ds_write_b32 v142, v140
; __device__ __forceinline__ float bf2f(unsigned b) { return __uint_as_float(b << 16); }
;     __device__ __forceinline__ void fused(f32x4 (&acc)[2][2][4][2], const Unit& u, int wr, int wc, int fr, int fq, LAS unsigned char* lds, int wid, int lane) const {
;     ...
;             for (int m = 0; m < 4; ++m) {
;                 const int r = ai * 128 + wr * 64 + m * 16 + fr; const size_t row = (size_t)u.pm * 256 + r;
;                 float ss = 0.f;
; #pragma unroll
;                 for (int bj = 0; bj < 2; ++bj) {
;                     const int col0 = u.pn * 256 + bj * 128 + wc * 32 + fq * 8;
;                     const v4u xb = __builtin_nontemporal_load((const v4u*)(XMIDB + row * D + col0));
;                     f32x4 v0 = acc[ai][bj][m][0], v1 = acc[ai][bj][m][1];
;                     v0[0] += bf2f(xb.x & 0xffffu); v0[1] += bf2f(xb.x >> 16); v0[2] += bf2f(xb.y & 0xffffu); v0[3] += bf2f(xb.y >> 16);
;                     v1[0] += bf2f(xb.z & 0xffffu); v1[1] += bf2f(xb.z >> 16); v1[2] += bf2f(xb.w & 0xffffu); v1[3] += bf2f(xb.w >> 16);
;                     acc[ai][bj][m][0] = v0; acc[ai][bj][m][1] = v1;
;                     ss += (v0[0] * v0[0] + v0[1] * v0[1]) + (v0[2] * v0[2] + v0[3] * v0[3]) + (v1[0] * v1[0] + v1[1] * v1[1]) + (v1[2] * v1[2] + v1[3] * v1[3]);
;                 }
;                 ss += __shfl_xor(ss, 16); ss += __shfl_xor(ss, 32);
;                 if (fq == 0) P[r * 4 + wc] = ss;
;                 if (m == 3) asm volatile("" ::: "memory");
.LBB0_1219:
	s_or_b64 exec, exec, s[2:3]
	v_add_u32_e32 v140, 0x90, v128
	s_waitcnt lgkmcnt(0)
	v_ashrrev_i32_e32 v141, 31, v140
	v_lshlrev_b64 v[142:143], 11, v[140:141]
	v_lshl_add_u64 v[142:143], s[0:1], 0, v[142:143]
	v_lshl_add_u64 v[146:147], v[130:131], 1, v[142:143]
	s_waitcnt vmcnt(4)
	v_mov_b32_e32 v142, v228
	v_mov_b32_e32 v143, v229
	v_mov_b32_e32 v144, v230
	v_mov_b32_e32 v145, v231
	v_mov_b32_e32 v146, v232
	v_mov_b32_e32 v147, v233
	v_mov_b32_e32 v148, v234
	v_mov_b32_e32 v149, v235
	v_lshlrev_b32_e32 v150, 16, v142
	v_and_b32_e32 v151, 0xffff0000, v142
	v_lshlrev_b32_e32 v154, 16, v143
	v_and_b32_e32 v155, 0xffff0000, v143
	v_lshlrev_b32_e32 v156, 16, v144
	v_and_b32_e32 v157, 0xffff0000, v144
	v_lshlrev_b32_e32 v158, 16, v146
	v_and_b32_e32 v159, 0xffff0000, v146
	v_lshlrev_b32_e32 v146, 16, v147
	v_and_b32_e32 v147, 0xffff0000, v147
	v_lshlrev_b32_e32 v144, 16, v145
	v_and_b32_e32 v145, 0xffff0000, v145
	v_lshlrev_b32_e32 v160, 16, v148
	v_and_b32_e32 v161, 0xffff0000, v148
	v_lshlrev_b32_e32 v148, 16, v149
	v_and_b32_e32 v149, 0xffff0000, v149
	v_pk_add_f32 v[142:143], v[44:45], v[150:151]
	v_pk_add_f32 v[46:47], v[46:47], v[154:155]
	v_pk_add_f32 v[44:45], v[40:41], v[156:157]
	v_pk_add_f32 v[40:41], v[36:37], v[158:159]
	v_pk_add_f32 v[38:39], v[38:39], v[146:147]
	v_pk_add_f32 v[42:43], v[42:43], v[144:145]
	v_pk_add_f32 v[36:37], v[32:33], v[160:161]
	v_pk_add_f32 v[32:33], v[34:35], v[148:149]
	v_pk_mul_f32 v[34:35], v[142:143], v[142:143]
	v_pk_mul_f32 v[144:145], v[46:47], v[46:47]
	v_pk_mul_f32 v[150:151], v[40:41], v[40:41]
	v_pk_mul_f32 v[154:155], v[38:39], v[38:39]
	v_pk_mul_f32 v[146:147], v[44:45], v[44:45]
	v_pk_mul_f32 v[156:157], v[36:37], v[36:37]
	v_add_f32_e32 v154, v154, v155
	v_add_f32_e32 v150, v150, v151
	v_add_f32_e32 v144, v144, v145
	v_add_f32_e32 v34, v34, v35
	v_pk_mul_f32 v[148:149], v[42:43], v[42:43]
	v_pk_mul_f32 v[158:159], v[32:33], v[32:33]
	v_add_f32_e32 v151, v156, v157
	v_add_f32_e32 v35, v146, v147
	v_add_f32_e32 v145, v150, v154
	v_add_f32_e32 v34, v34, v144
	v_add_f32_e32 v158, v158, v159
	v_add_f32_e32 v148, v148, v149
	v_add_f32_e32 v144, v151, v145
	v_add_f32_e32 v34, v35, v34
	v_add_f32_e32 v35, v158, v144
	v_add_f32_e32 v34, v148, v34
	v_add_f32_e32 v34, v34, v35
	ds_bpermute_b32 v35, v153, v34
	s_waitcnt lgkmcnt(0)
	v_add_f32_e32 v34, v34, v35
	ds_bpermute_b32 v35, v165, v34
	s_and_saveexec_b64 s[2:3], vcc
	s_cbranch_execz .LBB0_1221
	v_lshl_add_u32 v144, v140, 4, s14
	s_waitcnt lgkmcnt(0)
	v_add_f32_e32 v34, v34, v35
	ds_write_b32 v144, v34
; __device__ __forceinline__ float bf2f(unsigned b) { return __uint_as_float(b << 16); }
;     __device__ __forceinline__ void fused(f32x4 (&acc)[2][2][4][2], const Unit& u, int wr, int wc, int fr, int fq, LAS unsigned char* lds, int wid, int lane) const {
;     ...
;             for (int m = 0; m < 4; ++m) {
;                 const int r = ai * 128 + wr * 64 + m * 16 + fr; const size_t row = (size_t)u.pm * 256 + r;
;                 float ss = 0.f;
; #pragma unroll
;                 for (int bj = 0; bj < 2; ++bj) {
;                     const int col0 = u.pn * 256 + bj * 128 + wc * 32 + fq * 8;
;                     const v4u xb = __builtin_nontemporal_load((const v4u*)(XMIDB + row * D + col0));
;                     f32x4 v0 = acc[ai][bj][m][0], v1 = acc[ai][bj][m][1];
;                     v0[0] += bf2f(xb.x & 0xffffu); v0[1] += bf2f(xb.x >> 16); v0[2] += bf2f(xb.y & 0xffffu); v0[3] += bf2f(xb.y >> 16);
;                     v1[0] += bf2f(xb.z & 0xffffu); v1[1] += bf2f(xb.z >> 16); v1[2] += bf2f(xb.w & 0xffffu); v1[3] += bf2f(xb.w >> 16);
;                     acc[ai][bj][m][0] = v0; acc[ai][bj][m][1] = v1;
;                     ss += (v0[0] * v0[0] + v0[1] * v0[1]) + (v0[2] * v0[2] + v0[3] * v0[3]) + (v1[0] * v1[0] + v1[1] * v1[1]) + (v1[2] * v1[2] + v1[3] * v1[3]);
;                 }
;                 ss += __shfl_xor(ss, 16); ss += __shfl_xor(ss, 32);
;                 if (fq == 0) P[r * 4 + wc] = ss;
;                 if (m == 3) asm volatile("" ::: "memory");
.LBB0_1221:
	s_or_b64 exec, exec, s[2:3]
	v_add_u32_e32 v34, 0xa0, v128
	s_waitcnt lgkmcnt(0)
	v_ashrrev_i32_e32 v35, 31, v34
	v_lshlrev_b64 v[144:145], 11, v[34:35]
	v_lshl_add_u64 v[144:145], s[0:1], 0, v[144:145]
	v_lshl_add_u64 v[148:149], v[130:131], 1, v[144:145]
	s_waitcnt vmcnt(2)
	v_mov_b32_e32 v144, v236
	v_mov_b32_e32 v145, v237
	v_mov_b32_e32 v146, v238
	v_mov_b32_e32 v147, v239
	v_mov_b32_e32 v148, v240
	v_mov_b32_e32 v149, v241
	v_mov_b32_e32 v150, v242
	v_mov_b32_e32 v151, v243
	v_lshlrev_b32_e32 v154, 16, v144
	v_and_b32_e32 v155, 0xffff0000, v144
	v_lshlrev_b32_e32 v144, 16, v145
	v_and_b32_e32 v145, 0xffff0000, v145
	v_lshlrev_b32_e32 v158, 16, v148
	v_and_b32_e32 v159, 0xffff0000, v148
	v_lshlrev_b32_e32 v148, 16, v149
	v_and_b32_e32 v149, 0xffff0000, v149
	v_lshlrev_b32_e32 v156, 16, v146
	v_and_b32_e32 v157, 0xffff0000, v146
	v_lshlrev_b32_e32 v146, 16, v147
	v_and_b32_e32 v147, 0xffff0000, v147
	v_lshlrev_b32_e32 v160, 16, v150
	v_and_b32_e32 v161, 0xffff0000, v150
	v_pk_add_f32 v[28:29], v[28:29], v[154:155]
	v_pk_add_f32 v[30:31], v[30:31], v[144:145]
	v_pk_add_f32 v[20:21], v[20:21], v[158:159]
	v_pk_add_f32 v[22:23], v[22:23], v[148:149]
	v_lshlrev_b32_e32 v150, 16, v151
	v_and_b32_e32 v151, 0xffff0000, v151
	v_pk_add_f32 v[24:25], v[24:25], v[156:157]
	v_pk_add_f32 v[26:27], v[26:27], v[146:147]
	v_pk_add_f32 v[16:17], v[16:17], v[160:161]
	v_pk_mul_f32 v[144:145], v[28:29], v[28:29]
	v_pk_mul_f32 v[146:147], v[30:31], v[30:31]
	v_pk_mul_f32 v[154:155], v[20:21], v[20:21]
	v_pk_mul_f32 v[156:157], v[22:23], v[22:23]
	v_pk_add_f32 v[18:19], v[18:19], v[150:151]
	v_pk_mul_f32 v[148:149], v[24:25], v[24:25]
	v_pk_mul_f32 v[158:159], v[16:17], v[16:17]
	v_add_f32_e32 v156, v156, v157
	v_add_f32_e32 v154, v154, v155
	v_add_f32_e32 v146, v146, v147
	v_add_f32_e32 v144, v144, v145
	v_pk_mul_f32 v[150:151], v[26:27], v[26:27]
	v_pk_mul_f32 v[160:161], v[18:19], v[18:19]
	v_add_f32_e32 v155, v158, v159
	v_add_f32_e32 v145, v148, v149
	v_add_f32_e32 v147, v154, v156
	v_add_f32_e32 v144, v144, v146
	v_add_f32_e32 v160, v160, v161
	v_add_f32_e32 v150, v150, v151
	v_add_f32_e32 v146, v155, v147
	v_add_f32_e32 v144, v145, v144
	v_add_f32_e32 v145, v160, v146
	v_add_f32_e32 v144, v150, v144
	v_add_f32_e32 v144, v144, v145
	ds_bpermute_b32 v145, v153, v144
	s_waitcnt lgkmcnt(0)
	v_add_f32_e32 v144, v144, v145
	ds_bpermute_b32 v145, v165, v144
	s_and_saveexec_b64 s[2:3], vcc
	s_cbranch_execz .LBB0_1223
	v_lshl_add_u32 v146, v34, 4, s14
	s_waitcnt lgkmcnt(0)
	v_add_f32_e32 v144, v144, v145
	ds_write_b32 v146, v144
.LBB0_1223:
	s_or_b64 exec, exec, s[2:3]
	v_add_u32_e32 v144, 0xb0, v128
	s_waitcnt lgkmcnt(0)
	v_ashrrev_i32_e32 v145, 31, v144
	v_lshlrev_b64 v[146:147], 11, v[144:145]
	v_lshl_add_u64 v[146:147], s[0:1], 0, v[146:147]
	v_lshl_add_u64 v[150:151], v[130:131], 1, v[146:147]
	s_waitcnt vmcnt(0)
	v_mov_b32_e32 v146, v244
	v_mov_b32_e32 v147, v245
	v_mov_b32_e32 v148, v246
	v_mov_b32_e32 v149, v247
	v_mov_b32_e32 v154, v248
	v_mov_b32_e32 v155, v249
	v_mov_b32_e32 v156, v250
	v_mov_b32_e32 v157, v251
	v_lshlrev_b32_e32 v150, 16, v146
	v_and_b32_e32 v151, 0xffff0000, v146
	v_lshlrev_b32_e32 v146, 16, v147
	v_and_b32_e32 v147, 0xffff0000, v147
	v_lshlrev_b32_e32 v166, 16, v154
	v_and_b32_e32 v167, 0xffff0000, v154
	v_lshlrev_b32_e32 v154, 16, v155
	v_and_b32_e32 v155, 0xffff0000, v155
	v_lshlrev_b32_e32 v158, 16, v148
	v_and_b32_e32 v159, 0xffff0000, v148
	v_lshlrev_b32_e32 v148, 16, v149
	v_and_b32_e32 v149, 0xffff0000, v149
	v_lshlrev_b32_e32 v168, 16, v156
	v_and_b32_e32 v169, 0xffff0000, v156
	v_lshlrev_b32_e32 v170, 16, v157
	v_and_b32_e32 v171, 0xffff0000, v157
	v_pk_add_f32 v[160:161], v[12:13], v[150:151]
	v_pk_add_f32 v[162:163], v[14:15], v[146:147]
	v_pk_add_f32 v[150:151], v[4:5], v[166:167]
	v_pk_add_f32 v[154:155], v[6:7], v[154:155]
	v_pk_add_f32 v[156:157], v[8:9], v[158:159]
	v_pk_add_f32 v[158:159], v[10:11], v[148:149]
	v_pk_add_f32 v[146:147], v[0:1], v[168:169]
	v_pk_add_f32 v[148:149], v[2:3], v[170:171]
	v_pk_mul_f32 v[0:1], v[160:161], v[160:161]
	v_pk_mul_f32 v[2:3], v[162:163], v[162:163]
	v_pk_mul_f32 v[8:9], v[150:151], v[150:151]
	v_pk_mul_f32 v[10:11], v[154:155], v[154:155]
	v_pk_mul_f32 v[4:5], v[156:157], v[156:157]
	v_pk_mul_f32 v[12:13], v[146:147], v[146:147]
	v_add_f32_e32 v10, v10, v11
	v_add_f32_e32 v8, v8, v9
	v_add_f32_e32 v2, v2, v3
	v_add_f32_e32 v0, v0, v1
	v_pk_mul_f32 v[6:7], v[158:159], v[158:159]
	v_pk_mul_f32 v[14:15], v[148:149], v[148:149]
	v_add_f32_e32 v9, v12, v13
	v_add_f32_e32 v1, v4, v5
	v_add_f32_e32 v3, v8, v10
	v_add_f32_e32 v0, v0, v2
	v_add_f32_e32 v14, v14, v15
	v_add_f32_e32 v6, v6, v7
	v_add_f32_e32 v2, v9, v3
	v_add_f32_e32 v0, v1, v0
	v_add_f32_e32 v1, v14, v2
	v_add_f32_e32 v0, v6, v0
	v_add_f32_e32 v0, v0, v1
	ds_bpermute_b32 v1, v153, v0
	s_waitcnt lgkmcnt(0)
	v_add_f32_e32 v0, v0, v1
	ds_bpermute_b32 v1, v165, v0
	s_and_saveexec_b64 s[0:1], vcc
	s_cbranch_execz .LBB0_1225
	v_lshl_add_u32 v2, v144, 4, s14
	s_waitcnt lgkmcnt(0)
	v_add_f32_e32 v0, v0, v1
	ds_write_b32 v2, v0
